# one static s_setprio 1 for waves 4-7 inside memory-attention and sliding-window units (P2,P6), reset to 0 at the queue loop head
# baseline (speedup 1.0000x reference)
.LBB0_510:
	s_setprio 0
	s_and_saveexec_b64 s[0:1], s[96:97]
	s_cbranch_execz .LBB0_514
	s_mov_b64 s[6:7], exec
	v_mbcnt_lo_u32_b32 v0, s6, 0
	v_mbcnt_hi_u32_b32 v0, s7, v0
	v_cmp_eq_u32_e32 vcc, 0, v0
	s_and_saveexec_b64 s[4:5], vcc
	s_cbranch_execz .LBB0_513
	s_bcnt1_i32_b64 s6, s[6:7]
	v_mov_b32_e32 v2, s6
	global_atomic_add v2, v1, v2, s[30:31] sc0

.LBB0_537:
	v_readfirstlane_b32 s100, v180
	s_nop 1
	s_cmp_gt_u32 s100, 0xff
	s_cbranch_scc0 .Lprio_s0
	s_setprio 1

.LBB0_1287:
	s_setprio 0
	s_and_saveexec_b64 s[0:1], s[96:97]
	s_cbranch_execz .LBB0_1291
	s_mov_b64 s[6:7], exec
	v_mbcnt_lo_u32_b32 v0, s6, 0
	v_mbcnt_hi_u32_b32 v0, s7, v0
	v_cmp_eq_u32_e32 vcc, 0, v0
	s_and_saveexec_b64 s[4:5], vcc
	s_cbranch_execz .LBB0_1290
	s_bcnt1_i32_b64 s6, s[6:7]
	v_mov_b32_e32 v1, s6
	global_atomic_add v1, v161, v1, s[24:25] offset:256 sc0

	.amdhsa_kernel _Z8yoco_fwd4Args
		.amdhsa_group_segment_fixed_size 0
		.amdhsa_private_segment_fixed_size 0
		.amdhsa_kernarg_size 464
		.amdhsa_user_sgpr_count 2
		.amdhsa_user_sgpr_dispatch_ptr 0
		.amdhsa_user_sgpr_queue_ptr 0
		.amdhsa_user_sgpr_kernarg_segment_ptr 1
		.amdhsa_user_sgpr_dispatch_id 0
		.amdhsa_user_sgpr_kernarg_preload_length 0
		.amdhsa_user_sgpr_kernarg_preload_offset 0
		.amdhsa_user_sgpr_private_segment_size 0
		.amdhsa_uses_dynamic_stack 0
		.amdhsa_enable_private_segment 0
		.amdhsa_system_sgpr_workgroup_id_x 1
		.amdhsa_system_sgpr_workgroup_id_y 0
		.amdhsa_system_sgpr_workgroup_id_z 0
		.amdhsa_system_sgpr_workgroup_info 0
		.amdhsa_system_vgpr_workitem_id 2
		.amdhsa_next_free_vgpr 256
		.amdhsa_next_free_sgpr 102
		.amdhsa_accum_offset 256
		.amdhsa_reserve_vcc 1
		.amdhsa_float_round_mode_32 0
		.amdhsa_float_round_mode_16_64 0
		.amdhsa_float_denorm_mode_32 3
		.amdhsa_float_denorm_mode_16_64 3
		.amdhsa_dx10_clamp 1
		.amdhsa_ieee_mode 1
		.amdhsa_fp16_overflow 0
		.amdhsa_tg_split 0
		.amdhsa_exception_fp_ieee_invalid_op 0
		.amdhsa_exception_fp_denorm_src 0
		.amdhsa_exception_fp_ieee_div_zero 0
		.amdhsa_exception_fp_ieee_overflow 0
		.amdhsa_exception_fp_ieee_underflow 0
		.amdhsa_exception_fp_ieee_inexact 0
		.amdhsa_exception_int_div_zero 0
	.end_amdhsa_kernel

amdhsa.kernels:
  - .agpr_count:     0
    .args:
      - .offset:         0
        .size:           208
        .value_kind:     by_value
      - .offset:         208
        .size:           4
        .value_kind:     hidden_block_count_x
      - .offset:         212
        .size:           4
        .value_kind:     hidden_block_count_y
      - .offset:         216
        .size:           4
        .value_kind:     hidden_block_count_z
      - .offset:         220
        .size:           2
        .value_kind:     hidden_group_size_x
      - .offset:         222
        .size:           2
        .value_kind:     hidden_group_size_y
      - .offset:         224
        .size:           2
        .value_kind:     hidden_group_size_z
      - .offset:         226
        .size:           2
        .value_kind:     hidden_remainder_x
      - .offset:         228
        .size:           2
        .value_kind:     hidden_remainder_y
      - .offset:         230
        .size:           2
        .value_kind:     hidden_remainder_z
      - .offset:         248
        .size:           8
        .value_kind:     hidden_global_offset_x
      - .offset:         256
        .size:           8
        .value_kind:     hidden_global_offset_y
      - .offset:         264
        .size:           8
        .value_kind:     hidden_global_offset_z
      - .offset:         272
        .size:           2
        .value_kind:     hidden_grid_dims
      - .offset:         296
        .size:           8
        .value_kind:     hidden_multigrid_sync_arg
      - .offset:         328
        .size:           4
        .value_kind:     hidden_dynamic_lds_size
    .group_segment_fixed_size: 0
    .kernarg_segment_align: 8
    .kernarg_segment_size: 464
    .language:       OpenCL C
    .language_version:
      - 2
      - 0
    .max_flat_workgroup_size: 512
    .name:           _Z8yoco_fwd4Args
    .private_segment_fixed_size: 0
    .sgpr_count:     108
    .sgpr_spill_count: 195
    .symbol:         _Z8yoco_fwd4Args.kd
    .uniform_work_group_size: 1
    .uses_dynamic_stack: false
    .vgpr_count:     256
    .vgpr_spill_count: 0
    .wavefront_size: 64
